# attention: first K/V tile of each unit loaded together with Q (before the Q wait)
# baseline (speedup 1.0000x reference)
; __device__ __forceinline__ float bf_lo(unsigned w) { return __uint_as_float(w << 16); }
; __device__ __forceinline__ float bf_hi(unsigned w) { return __uint_as_float(w & 0xffff0000u); }
; #define LOAD_TILE(ti, kreg, vreg) do { const int k0_ = TILE_K0(ti); const size_t grow_ = ((ti) < 4) ? (size_t)(M_ + b * LCTX + k0_) : (size_t)(b * SEQ + k0_); \
;         kreg = *(const u32x4*)(QKV + (grow_ + krow) * NQKV + 1024 + kvh * 64 + 8 * kch); vreg = *(const u32x4*)(QKV + (grow_ + lane) * NQKV + 1280 + kvh * 64 + 8 * w); } while (0)
; #define LOAD_TILE(ti, kreg, vreg) do { const int k0_ = TILE_K0(ti); const size_t grow_ = ((ti) < 4) ? (size_t)(M_ + b * LCTX + k0_) : (size_t)(b * SEQ + k0_); \
;         kreg = *(const u32x4*)(QKV + (grow_ + krow) * NQKV + 1024 + kvh * 64 + 8 * kch); vreg = *(const u32x4*)(QKV + (grow_ + lane) * NQKV + 1280 + kvh * 64 + 8 * w); } while (0)
;     ...
;         {
;             const bf16_t* qp = QKV + (size_t)(b * SEQ + qrow) * NQKV + head * 64;
;             float qf[4][8]; float ss = 0.f;
; #pragma unroll
;             for (int d0 = 0; d0 < 4; ++d0) { const u32x4 v = *(const u32x4*)(qp + 8 * (2 * d0 + hi));
;                 qf[d0][0] = bf_lo(v.x); qf[d0][1] = bf_hi(v.x); qf[d0][2] = bf_lo(v.y); qf[d0][3] = bf_hi(v.y); qf[d0][4] = bf_lo(v.z); qf[d0][5] = bf_hi(v.z); qf[d0][6] = bf_lo(v.w); qf[d0][7] = bf_hi(v.w);
; #pragma unroll
;                 for (int i = 0; i < 8; ++i) ss += qf[d0][i] * qf[d0][i]; }
;             ss += __shfl_xor(ss, 32);
;     ...
;         LOAD_TILE(0, kreg, vreg); STORE_TILE(0, 0); LOAD_TILE(1, kreg, vreg); LOAD_TILE(2, kreg2, vreg2); LOAD_TILE(3, kreg3, vreg3); __syncthreads();
.LBB0_503:
	s_lshl_b32 s8, s55, 6
	s_ashr_i32 s22, s55, 9
	s_bfe_u32 s25, s55, 0x20007
	s_and_b32 s13, s8, 0x1fc0
	s_lshl_b32 s8, s25, 2
	v_add_u32_e32 v146, s13, v175
	s_lshl_b32 s24, s22, 13
	s_or_b32 s38, s8, s11
	v_add_u32_e32 v170, s24, v146
	v_mad_i64_i32 v[0:1], s[40:41], v170, s46, v[160:161]
	s_lshl_b32 s8, s38, 7
	v_lshl_add_u64 v[0:1], v[0:1], 0, s[8:9]
	v_lshl_add_u64 v[0:1], v[0:1], 0, v[162:163]
	global_load_dwordx4 v[40:43], v[0:1], off offset:32
	global_load_dwordx4 v[44:47], v[0:1], off offset:96
	global_load_dwordx4 v[32:35], v[0:1], off
	global_load_dwordx4 v[28:31], v[0:1], off offset:64
	global_load_dwordx4 v[8:11], v[148:149], off offset:80
	global_load_dwordx4 v[12:15], v[148:149], off offset:64
	s_nop 0
	global_load_dwordx4 v[0:3], v[148:149], off offset:208
	global_load_dwordx4 v[4:7], v[148:149], off offset:192
	global_load_dwordx4 v[24:27], v[148:149], off offset:16
	global_load_dwordx4 v[36:39], v[148:149], off
	global_load_dwordx4 v[16:19], v[148:149], off offset:144
	s_waitcnt lgkmcnt(0)
	global_load_dwordx4 v[20:23], v[148:149], off offset:128
	v_lshlrev_b64 v[48:49], 8, v[146:147]
	s_lshl_b32 s8, s38, 2
	v_readlane_b32 s72, v255, 4
	v_lshl_add_u64 v[72:73], v[156:157], 0, v[48:49]
	v_mov_b32_e32 v76, s8
	v_readlane_b32 s80, v255, 12
	v_readlane_b32 s81, v255, 13
	global_load_dwordx4 v[48:51], v[72:73], off offset:64
	global_load_dwordx4 v[52:55], v[72:73], off offset:192
	global_load_dwordx4 v[56:59], v[72:73], off offset:16
	global_load_dwordx4 v[60:63], v[72:73], off
	global_load_dwordx4 v[64:67], v[72:73], off offset:144
	global_load_dwordx4 v[68:71], v[72:73], off offset:128
	global_load_dword v124, v76, s[80:81]
	s_lshl_b32 s39, s22, 8
	s_add_i32 s22, s39, 0x10000
	s_ashr_i32 s23, s22, 31
	v_lshl_add_u64 v[74:75], s[22:23], 0, v[154:155]
	s_lshl_b32 s8, s25, 7
	v_readlane_b32 s73, v255, 5
	v_readlane_b32 s74, v255, 6
	v_readlane_b32 s75, v255, 7
	v_readlane_b32 s76, v255, 8
	v_readlane_b32 s77, v255, 9
	v_readlane_b32 s78, v255, 10
	v_readlane_b32 s79, v255, 11
	v_readlane_b32 s82, v255, 14
	v_readlane_b32 s83, v255, 15
	v_readlane_b32 s84, v255, 16
	v_readlane_b32 s85, v255, 17
	v_readlane_b32 s86, v255, 18
	v_readlane_b32 s87, v255, 19
	v_mad_u64_u32 v[190:191], s[40:41], v74, s46, v[160:161]
	v_mad_i32_i24 v191, v75, s46, v191
	v_lshl_add_u64 v[190:191], v[190:191], 0, s[8:9]
	v_or_b32_e32 v242, s22, v144
	v_mad_i64_i32 v[242:243], s[40:41], v242, s46, v[160:161]
	v_lshl_add_u64 v[242:243], v[242:243], 0, s[8:9]
	v_lshl_add_u64 v[190:191], v[190:191], 0, v[168:169]
	v_lshl_add_u64 v[242:243], v[242:243], 0, s[20:21]
	global_load_dwordx4 v[244:247], v[190:191], off offset:2048
	global_load_dwordx4 v[248:251], v[242:243], off offset:2560
	s_waitcnt vmcnt(0)
	v_lshlrev_b32_e32 v86, 16, v40
	v_and_b32_e32 v87, 0xffff0000, v40
	v_lshlrev_b32_e32 v100, 16, v32
	v_and_b32_e32 v101, 0xffff0000, v32
	v_lshlrev_b32_e32 v96, 16, v33
	v_and_b32_e32 v97, 0xffff0000, v33
	v_pk_mul_f32 v[120:121], v[100:101], v[100:101]
	v_pk_mul_f32 v[116:117], v[96:97], v[96:97]
	v_add_f32_e32 v120, v120, v121
	v_lshlrev_b32_e32 v92, 16, v34
	v_and_b32_e32 v93, 0xffff0000, v34
	v_add_f32_e32 v116, v116, v120
	v_pk_mul_f32 v[112:113], v[92:93], v[92:93]
	v_add_f32_e32 v116, v117, v116
	v_lshlrev_b32_e32 v88, 16, v35
	v_and_b32_e32 v89, 0xffff0000, v35
	v_add_f32_e32 v112, v112, v116
	v_pk_mul_f32 v[108:109], v[88:89], v[88:89]
	v_add_f32_e32 v112, v113, v112
	v_add_f32_e32 v108, v108, v112
	v_pk_mul_f32 v[104:105], v[86:87], v[86:87]
	v_add_f32_e32 v108, v109, v108
	v_lshlrev_b32_e32 v78, 16, v47
	v_and_b32_e32 v79, 0xffff0000, v47
	v_lshlrev_b32_e32 v82, 16, v46
	v_and_b32_e32 v83, 0xffff0000, v46
	v_lshlrev_b32_e32 v46, 16, v41
	v_and_b32_e32 v47, 0xffff0000, v41
	v_add_f32_e32 v104, v104, v108
	v_lshlrev_b32_e32 v76, 16, v43
	v_and_b32_e32 v77, 0xffff0000, v43
	v_lshlrev_b32_e32 v80, 16, v42
	v_and_b32_e32 v81, 0xffff0000, v42
	v_pk_mul_f32 v[42:43], v[46:47], v[46:47]
	v_add_f32_e32 v104, v105, v104
	v_add_f32_e32 v42, v42, v104
	v_pk_mul_f32 v[32:33], v[80:81], v[80:81]
	v_add_f32_e32 v42, v43, v42
	v_add_f32_e32 v32, v32, v42
	v_lshlrev_b32_e32 v98, 16, v29
	v_and_b32_e32 v99, 0xffff0000, v29
	v_lshlrev_b32_e32 v102, 16, v28
	v_and_b32_e32 v103, 0xffff0000, v28
	v_pk_mul_f32 v[28:29], v[76:77], v[76:77]
	v_add_f32_e32 v32, v33, v32
	v_add_f32_e32 v28, v28, v32
	v_pk_mul_f32 v[122:123], v[102:103], v[102:103]
	v_add_f32_e32 v28, v29, v28
	v_add_f32_e32 v28, v122, v28
	v_pk_mul_f32 v[118:119], v[98:99], v[98:99]
	v_add_f32_e32 v28, v123, v28
	v_lshlrev_b32_e32 v94, 16, v30
	v_and_b32_e32 v95, 0xffff0000, v30
	v_add_f32_e32 v28, v118, v28
	v_pk_mul_f32 v[114:115], v[94:95], v[94:95]
	v_add_f32_e32 v28, v119, v28
	v_lshlrev_b32_e32 v90, 16, v31
	v_and_b32_e32 v91, 0xffff0000, v31
	v_add_f32_e32 v28, v114, v28
	v_pk_mul_f32 v[110:111], v[90:91], v[90:91]
	v_add_f32_e32 v28, v115, v28
	v_lshlrev_b32_e32 v40, 16, v44
	v_and_b32_e32 v41, 0xffff0000, v44
	v_add_f32_e32 v28, v110, v28
	v_pk_mul_f32 v[106:107], v[40:41], v[40:41]
	v_add_f32_e32 v28, v111, v28
	v_lshlrev_b32_e32 v84, 16, v45
	v_and_b32_e32 v85, 0xffff0000, v45
	v_add_f32_e32 v28, v106, v28
	v_pk_mul_f32 v[44:45], v[84:85], v[84:85]
	v_add_f32_e32 v28, v107, v28
	v_add_f32_e32 v28, v44, v28
	v_pk_mul_f32 v[34:35], v[82:83], v[82:83]
	v_add_f32_e32 v28, v45, v28
	v_add_f32_e32 v28, v34, v28
	v_pk_mul_f32 v[30:31], v[78:79], v[78:79]
	v_add_f32_e32 v28, v35, v28
	v_add_f32_e32 v28, v30, v28
	v_add_f32_e32 v30, v31, v28
	ds_bpermute_b32 v31, v176, v30
	s_waitcnt lgkmcnt(0)
; __device__ __forceinline__ unsigned pk2(float lo, float hi) { f32x2 v = {lo, hi}; bf16x2_t b = __builtin_convertvector(v, bf16x2_t); return __builtin_bit_cast(unsigned, b); }
; #define LOAD_TILE(ti, kreg, vreg) do { const int k0_ = TILE_K0(ti); const size_t grow_ = ((ti) < 4) ? (size_t)(M_ + b * LCTX + k0_) : (size_t)(b * SEQ + k0_); \
;         kreg = *(const u32x4*)(QKV + (grow_ + krow) * NQKV + 1024 + kvh * 64 + 8 * kch); vreg = *(const u32x4*)(QKV + (grow_ + lane) * NQKV + 1280 + kvh * 64 + 8 * w); } while (0)
; #define LOAD_TILE(ti, kreg, vreg) do { const int k0_ = TILE_K0(ti); const size_t grow_ = ((ti) < 4) ? (size_t)(M_ + b * LCTX + k0_) : (size_t)(b * SEQ + k0_); \
;         kreg = *(const u32x4*)(QKV + (grow_ + krow) * NQKV + 1024 + kvh * 64 + 8 * kch); vreg = *(const u32x4*)(QKV + (grow_ + lane) * NQKV + 1280 + kvh * 64 + 8 * w); } while (0)
;     ...
;             const float rstd = rsqrtf(ss * (1.0f / 64.0f) + 1e-6f);
; #pragma unroll
;             for (int d0 = 0; d0 < 4; ++d0)
; #pragma unroll
;                 for (int i = 0; i < 8; ++i) qf[d0][i] *= rstd * qgain[8 * (2 * d0 + hi) + i];
;             const float* rp = ROPE + (size_t)qrow * 64;
;             float qo[4][8];
; #pragma unroll
;             for (int d0 = 0; d0 < 2; ++d0)
; #pragma unroll
;                 for (int i = 0; i < 8; ++i) { const int j = 8 * (2 * d0 + hi) + i; const float cs = rp[j], sn = rp[32 + j];
;                     qo[d0][i] = qf[d0][i] * cs - qf[d0 + 2][i] * sn; qo[d0 + 2][i] = qf[d0][i] * sn + qf[d0 + 2][i] * cs; }
; #pragma unroll
;             for (int d0 = 0; d0 < 4; ++d0) { u32x4 pw; pw.x = pk2(qo[d0][0] * C2, qo[d0][1] * C2); pw.y = pk2(qo[d0][2] * C2, qo[d0][3] * C2); pw.z = pk2(qo[d0][4] * C2, qo[d0][5] * C2); pw.w = pk2(qo[d0][6] * C2, qo[d0][7] * C2);
;                 qr[d0] = __builtin_bit_cast(bf16x8, pw); }
;     ...
;         LOAD_TILE(0, kreg, vreg); STORE_TILE(0, 0); LOAD_TILE(1, kreg, vreg); LOAD_TILE(2, kreg2, vreg2); LOAD_TILE(3, kreg3, vreg3); __syncthreads();
	v_add_f32_e32 v30, v30, v31
	v_fmamk_f32 v42, v30, 0x3c800000, v180
	v_mul_f32_e32 v43, 0x4b800000, v42
	v_cmp_gt_f32_e32 vcc, s47, v42
	s_add_i32 s22, s39, 0x10040
	s_ashr_i32 s23, s22, 31
	v_cndmask_b32_e32 v42, v42, v43, vcc
	v_rsq_f32_e32 v104, v42
	global_load_dwordx4 v[42:45], v[72:73], off offset:80
	s_nop 0
	global_load_dwordx4 v[72:75], v[72:73], off offset:208
	v_mul_f32_e32 v146, 0x3fb8aa3b, v124
	ds_write_b128 v177, v[244:247]
	ds_write_b16 v178, v248 offset:18432
	ds_write_b16_d16_hi v178, v248 offset:18568
	ds_write_b16 v178, v249 offset:18704
	ds_write_b16_d16_hi v178, v249 offset:18840
	ds_write_b16 v178, v250 offset:18976
	ds_write_b16_d16_hi v178, v250 offset:19112
	ds_write_b16 v178, v251 offset:19248
	ds_write_b16_d16_hi v178, v251 offset:19384
	v_mul_f32_e32 v105, 0x45800000, v104
	v_cndmask_b32_e32 v104, v104, v105, vcc
	v_pk_mul_f32 v[36:37], v[36:37], v[104:105] op_sel_hi:[1,0]
	v_pk_mul_f32 v[8:9], v[8:9], v[104:105] op_sel_hi:[1,0]
	v_pk_mul_f32 v[36:37], v[36:37], v[100:101]
	v_pk_mul_f32 v[100:101], v[8:9], v[80:81]
	v_pk_mul_f32 v[8:9], v[10:11], v[104:105] op_sel_hi:[1,0]
	v_pk_mul_f32 v[0:1], v[0:1], v[104:105] op_sel_hi:[1,0]
	v_pk_mul_f32 v[76:77], v[8:9], v[76:77]
	v_pk_mul_f32 v[8:9], v[20:21], v[104:105] op_sel_hi:[1,0]
	v_pk_mul_f32 v[38:39], v[38:39], v[104:105] op_sel_hi:[1,0]
	v_pk_mul_f32 v[12:13], v[12:13], v[104:105] op_sel_hi:[1,0]
	v_pk_mul_f32 v[8:9], v[8:9], v[102:103]
	v_pk_mul_f32 v[10:11], v[22:23], v[104:105] op_sel_hi:[1,0]
	v_pk_mul_f32 v[112:113], v[0:1], v[82:83]
	v_pk_mul_f32 v[0:1], v[2:3], v[104:105] op_sel_hi:[1,0]
	v_pk_mul_f32 v[38:39], v[38:39], v[96:97]
	v_pk_mul_f32 v[24:25], v[24:25], v[104:105] op_sel_hi:[1,0]
	v_pk_mul_f32 v[96:97], v[12:13], v[86:87]
	v_pk_mul_f32 v[12:13], v[14:15], v[104:105] op_sel_hi:[1,0]
	v_pk_mul_f32 v[10:11], v[10:11], v[98:99]
	v_pk_mul_f32 v[78:79], v[0:1], v[78:79]
	v_pk_mul_f32 v[0:1], v[60:61], v[8:9]
	v_pk_mul_f32 v[24:25], v[24:25], v[92:93]
	v_pk_mul_f32 v[26:27], v[26:27], v[104:105] op_sel_hi:[1,0]
	v_pk_mul_f32 v[46:47], v[12:13], v[46:47]
	v_pk_mul_f32 v[12:13], v[16:17], v[104:105] op_sel_hi:[1,0]
	v_pk_fma_f32 v[114:115], v[68:69], v[36:37], v[0:1]
	v_pk_mul_f32 v[0:1], v[62:63], v[10:11]
	v_pk_mul_f32 v[26:27], v[26:27], v[88:89]
	v_pk_mul_f32 v[12:13], v[12:13], v[94:95]
	v_pk_mul_f32 v[14:15], v[18:19], v[104:105] op_sel_hi:[1,0]
	v_pk_fma_f32 v[116:117], v[70:71], v[38:39], v[0:1]
	v_pk_mul_f32 v[0:1], v[64:65], v[24:25]
	v_pk_mul_f32 v[14:15], v[14:15], v[90:91]
	v_pk_fma_f32 v[118:119], v[56:57], v[12:13], v[0:1]
	v_pk_mul_f32 v[0:1], v[26:27], v[66:67]
	v_pk_mul_f32 v[4:5], v[4:5], v[104:105] op_sel_hi:[1,0]
	v_pk_fma_f32 v[120:121], v[14:15], v[58:59], v[0:1]
	v_pk_mul_f32 v[0:1], v[68:69], v[8:9]
	v_pk_mul_f32 v[98:99], v[4:5], v[40:41]
	v_pk_fma_f32 v[0:1], v[60:61], v[36:37], v[0:1] neg_lo:[0,0,1] neg_hi:[0,0,1]
	v_pk_mul_f32 v[4:5], v[6:7], v[104:105] op_sel_hi:[1,0]
	v_pk_mul_f32 v[0:1], v[0:1], s[10:11] op_sel_hi:[1,0]
	v_pk_mul_f32 v[102:103], v[4:5], v[84:85]
	v_cvt_pk_bf16_f32 v80, v0, v1
	v_pk_mul_f32 v[0:1], v[70:71], v[10:11]
	v_lshl_add_u64 v[10:11], s[22:23], 0, v[154:155]
	v_pk_fma_f32 v[0:1], v[62:63], v[38:39], v[0:1] neg_lo:[0,0,1] neg_hi:[0,0,1]
	v_pk_mul_f32 v[16:17], v[102:103], v[54:55]
	v_pk_mul_f32 v[0:1], v[0:1], s[10:11] op_sel_hi:[1,0]
	v_pk_fma_f32 v[16:17], v[46:47], v[50:51], v[16:17] neg_lo:[0,0,1] neg_hi:[0,0,1]
	v_cvt_pk_bf16_f32 v81, v0, v1
	v_pk_mul_f32 v[0:1], v[12:13], v[64:65]
	v_mad_u64_u32 v[12:13], s[40:41], v10, s46, v[160:161]
	v_mad_i32_i24 v13, v11, s46, v13
	v_lshl_add_u64 v[10:11], v[12:13], 0, s[8:9]
	v_or_b32_e32 v12, s22, v144
	v_mad_i64_i32 v[12:13], s[22:23], v12, s46, v[160:161]
	s_add_i32 s22, s39, 0x10080
	v_lshl_add_u64 v[10:11], v[10:11], 0, v[168:169]
	v_lshl_add_u64 v[12:13], v[12:13], 0, s[8:9]
	s_ashr_i32 s23, s22, 31
	v_lshl_add_u64 v[12:13], v[12:13], 0, s[20:21]
	global_load_dwordx4 v[38:41], v[10:11], off offset:2048
	global_load_dwordx4 v[34:37], v[12:13], off offset:2560
	v_lshl_add_u64 v[10:11], s[22:23], 0, v[154:155]
	v_mad_u64_u32 v[12:13], s[40:41], v10, s46, v[160:161]
	v_mad_i32_i24 v13, v11, s46, v13
	v_lshl_add_u64 v[10:11], v[12:13], 0, s[8:9]
	v_or_b32_e32 v12, s22, v144
	v_mad_i64_i32 v[12:13], s[22:23], v12, s46, v[160:161]
	s_add_i32 s22, s39, 0x100c0
	v_lshl_add_u64 v[10:11], v[10:11], 0, v[168:169]
	v_lshl_add_u64 v[12:13], v[12:13], 0, s[8:9]
	s_ashr_i32 s23, s22, 31
	v_lshl_add_u64 v[12:13], v[12:13], 0, s[20:21]
	global_load_dwordx4 v[108:111], v[10:11], off offset:2048
	global_load_dwordx4 v[104:107], v[12:13], off offset:2560
	v_lshl_add_u64 v[10:11], s[22:23], 0, v[154:155]
	v_mad_u64_u32 v[12:13], s[40:41], v10, s46, v[160:161]
	v_mad_i32_i24 v13, v11, s46, v13
	v_lshl_add_u64 v[10:11], v[12:13], 0, s[8:9]
	v_or_b32_e32 v12, s22, v144
	v_mad_i64_i32 v[12:13], s[22:23], v12, s46, v[160:161]
	v_lshl_add_u64 v[10:11], v[10:11], 0, v[168:169]
	v_lshl_add_u64 v[12:13], v[12:13], 0, s[8:9]
	v_pk_fma_f32 v[0:1], v[24:25], v[56:57], v[0:1] neg_lo:[0,0,1] neg_hi:[0,0,1]
	v_lshl_add_u64 v[12:13], v[12:13], 0, s[20:21]
	global_load_dwordx4 v[88:91], v[10:11], off offset:2048
	global_load_dwordx4 v[92:95], v[12:13], off offset:2560
	v_pk_mul_f32 v[0:1], v[0:1], s[10:11] op_sel_hi:[1,0]
	s_waitcnt lgkmcnt(0)
	v_cvt_pk_bf16_f32 v82, v0, v1
	v_pk_mul_f32 v[0:1], v[14:15], v[66:67]
	s_barrier
; __device__ __forceinline__ unsigned pk2(float lo, float hi) { f32x2 v = {lo, hi}; bf16x2_t b = __builtin_convertvector(v, bf16x2_t); return __builtin_bit_cast(unsigned, b); }
;     ...
; #pragma unroll
;             for (int d0 = 0; d0 < 4; ++d0) { u32x4 pw; pw.x = pk2(qo[d0][0] * C2, qo[d0][1] * C2); pw.y = pk2(qo[d0][2] * C2, qo[d0][3] * C2); pw.z = pk2(qo[d0][4] * C2, qo[d0][5] * C2); pw.w = pk2(qo[d0][6] * C2, qo[d0][7] * C2);
;                 qr[d0] = __builtin_bit_cast(bf16x8, pw); }
	v_pk_fma_f32 v[0:1], v[26:27], v[58:59], v[0:1] neg_lo:[0,0,1] neg_hi:[0,0,1]
	ds_read_b128 v[56:59], v145
	v_pk_mul_f32 v[0:1], v[0:1], s[10:11] op_sel_hi:[1,0]
	ds_read_b128 v[60:63], v145 offset:4608
	ds_read_b128 v[64:67], v145 offset:32
	v_cvt_pk_bf16_f32 v83, v0, v1
	v_pk_mul_f32 v[0:1], v[98:99], v[52:53]
	v_pk_mul_f32 v[16:17], v[16:17], s[10:11] op_sel_hi:[1,0]
	v_pk_fma_f32 v[0:1], v[96:97], v[48:49], v[0:1] neg_lo:[0,0,1] neg_hi:[0,0,1]
	v_cvt_pk_bf16_f32 v85, v16, v17
	v_pk_mul_f32 v[0:1], v[0:1], s[10:11] op_sel_hi:[1,0]
	s_waitcnt vmcnt(6)
	v_pk_mul_f32 v[68:69], v[112:113], v[72:73]
	v_cvt_pk_bf16_f32 v84, v0, v1
	v_xor_b32_e32 v0, 0x80000000, v146
	v_mov_b32_e32 v1, v0
	v_mov_b32_e32 v2, v0
	v_mov_b32_e32 v3, v0
	v_mov_b32_e32 v4, v0
	v_mov_b32_e32 v5, v0
	v_mov_b32_e32 v6, v0
	v_mov_b32_e32 v7, v0
	v_mov_b32_e32 v8, v0
	v_mov_b32_e32 v9, v0
	v_mov_b32_e32 v10, v0
	v_mov_b32_e32 v11, v0
	v_mov_b32_e32 v12, v0
	v_mov_b32_e32 v13, v0
	v_mov_b32_e32 v14, v0
	v_mov_b32_e32 v15, v0
	v_pk_mul_f32 v[52:53], v[96:97], v[52:53]
	s_waitcnt lgkmcnt(2)
	v_mfma_f32_32x32x16_bf16 v[18:33], v[56:59], v[80:83], v[0:15]
	v_mov_b64_e32 v[16:17], v[14:15]
	ds_read_b128 v[56:59], v145 offset:4640
	s_nop 4
	v_mov_b64_e32 v[14:15], v[12:13]
	v_mov_b64_e32 v[12:13], v[10:11]
	v_mov_b64_e32 v[10:11], v[8:9]
	v_mov_b64_e32 v[8:9], v[6:7]
	v_mov_b64_e32 v[6:7], v[4:5]
	v_mov_b64_e32 v[4:5], v[2:3]
	v_mov_b64_e32 v[2:3], v[0:1]
	s_waitcnt lgkmcnt(2)
	s_nop 0
	v_mfma_f32_32x32x16_bf16 v[2:17], v[60:63], v[80:83], v[2:17]
	v_fma_f32 v60, v100, v42, -v68
	v_fma_f32 v61, v101, v43, -v69
	v_mul_f32_e64 v62, v46, v54
	v_mul_f32_e64 v63, v47, v55
	v_mul_f32_e64 v60, v60, s10
	v_mul_f32_e64 v61, v61, s10
	v_pk_mul_f32 v[46:47], v[114:115], s[10:11] op_sel_hi:[1,0]
	v_cvt_pk_bf16_f32 v86, v60, v61
	v_pk_mul_f32 v[60:61], v[78:79], v[74:75]
	v_cvt_pk_bf16_f32 v96, v46, v47
	v_pk_fma_f32 v[60:61], v[76:77], v[44:45], v[60:61] neg_lo:[0,0,1] neg_hi:[0,0,1]
	s_nop 0
	v_pk_mul_f32 v[60:61], v[60:61], s[10:11] op_sel_hi:[1,0]
	s_nop 0
	v_cvt_pk_bf16_f32 v87, v60, v61
	v_pk_fma_f32 v[60:61], v[98:99], v[48:49], v[52:53]
	ds_read_b128 v[46:49], v145 offset:64
	s_waitcnt lgkmcnt(2)
	v_mfma_f32_32x32x16_bf16 v[18:33], v[64:67], v[84:87], v[18:33]
	v_mul_f32_e64 v52, v116, s10
	v_mul_f32_e64 v53, v117, s10
	v_mul_f32_e64 v60, v60, s10
	v_mul_f32_e64 v61, v61, s10
	v_cvt_pk_bf16_f32 v97, v52, v53
	v_pk_mul_f32 v[52:53], v[118:119], s[10:11] op_sel_hi:[1,0]
	s_nop 0
	v_cvt_pk_bf16_f32 v98, v52, v53
	v_pk_mul_f32 v[52:53], v[120:121], s[10:11] op_sel_hi:[1,0]
	s_waitcnt lgkmcnt(1)
	v_mfma_f32_32x32x16_bf16 v[2:17], v[56:59], v[84:87], v[2:17]
	v_cvt_pk_bf16_f32 v99, v52, v53
	ds_read_b128 v[52:55], v145 offset:4672
	ds_read_b128 v[56:59], v145 offset:96
	s_waitcnt lgkmcnt(2)
	v_mfma_f32_32x32x16_bf16 v[18:33], v[46:49], v[96:99], v[18:33]
	v_mul_f32_e64 v48, v100, v72
	v_mul_f32_e64 v49, v101, v73
	v_fma_f32 v46, v102, v50, v62
	v_fma_f32 v47, v103, v51, v63
	v_fma_f32 v48, v112, v42, v48
	v_fma_f32 v49, v113, v43, v49
	v_pk_mul_f32 v[42:43], v[76:77], v[74:75]
	v_pk_mul_f32 v[46:47], v[46:47], s[10:11] op_sel_hi:[1,0]
	v_pk_fma_f32 v[50:51], v[78:79], v[44:45], v[42:43]
	ds_read_b128 v[42:45], v145 offset:4704
	s_waitcnt lgkmcnt(2)
	v_mfma_f32_32x32x16_bf16 v[2:17], v[52:55], v[96:99], v[2:17]
	v_cvt_pk_bf16_f32 v101, v46, v47
	v_mul_f32_e64 v46, v48, s10
	v_mul_f32_e64 v47, v49, s10
	v_cvt_pk_bf16_f32 v100, v60, v61
	v_cvt_pk_bf16_f32 v102, v46, v47
	v_pk_mul_f32 v[46:47], v[50:51], s[10:11] op_sel_hi:[1,0]
	s_nop 0
	v_cvt_pk_bf16_f32 v103, v46, v47
	s_waitcnt lgkmcnt(1)
	s_nop 0
	v_mfma_f32_32x32x16_bf16 v[18:33], v[56:59], v[100:103], v[18:33]
	s_waitcnt lgkmcnt(0)
	v_mfma_f32_32x32x16_bf16 v[2:17], v[42:45], v[100:103], v[2:17]
	s_nop 9
	v_max_f32_e32 v42, v19, v19
	v_max_f32_e32 v43, v20, v20
	v_max_f32_e32 v44, v21, v21
	v_max_f32_e32 v1, v3, v3
	v_max_f32_e32 v1, v42, v1
	v_max_f32_e32 v42, v4, v4
	v_max_f32_e32 v42, v43, v42
	v_max_f32_e32 v43, v5, v5
	v_max3_f32 v1, v18, v2, v1
	v_max_f32_e32 v43, v44, v43
	v_max3_f32 v1, v1, v42, v43
	v_max_f32_e32 v42, v6, v6
	v_max_f32_e32 v43, v22, v22
	v_max_f32_e32 v42, v43, v42
	v_max_f32_e32 v43, v7, v7
	v_max_f32_e32 v44, v23, v23
	v_max_f32_e32 v43, v44, v43
	v_max3_f32 v1, v1, v42, v43
	v_max_f32_e32 v42, v8, v8
	v_max_f32_e32 v43, v24, v24
	v_max_f32_e32 v42, v43, v42
	v_max_f32_e32 v43, v9, v9
	v_max_f32_e32 v44, v25, v25
	v_max_f32_e32 v43, v44, v43
	v_max3_f32 v1, v1, v42, v43
	v_max_f32_e32 v42, v10, v10
	v_max_f32_e32 v43, v26, v26
	v_max_f32_e32 v42, v43, v42
	v_max_f32_e32 v43, v11, v11
	v_max_f32_e32 v44, v27, v27
	v_max_f32_e32 v43, v44, v43
	v_max3_f32 v1, v1, v42, v43
	v_max_f32_e32 v42, v12, v12
	v_max_f32_e32 v43, v28, v28
	v_max_f32_e32 v42, v43, v42
	v_max_f32_e32 v43, v13, v13
	v_max_f32_e32 v44, v29, v29
	v_max_f32_e32 v43, v44, v43
	v_max3_f32 v1, v1, v42, v43
	v_max_f32_e32 v42, v14, v14
	v_max_f32_e32 v43, v30, v30
	v_max_f32_e32 v42, v43, v42
	v_max_f32_e32 v43, v15, v15
	v_max_f32_e32 v44, v31, v31
	v_max_f32_e32 v43, v44, v43
	v_max3_f32 v1, v1, v42, v43
	v_max_f32_e32 v42, v16, v16
	v_max_f32_e32 v43, v32, v32
	v_max_f32_e32 v42, v43, v42
	v_max_f32_e32 v43, v17, v17
	v_max_f32_e32 v44, v33, v33
	v_max_f32_e32 v43, v44, v43
	v_max3_f32 v1, v1, v42, v43
	ds_bpermute_b32 v42, v176, v1
	s_waitcnt lgkmcnt(0)
	v_max_f32_e32 v42, v42, v42
	v_max_f32_e32 v1, v1, v42
	v_cmp_lt_f32_e32 vcc, s52, v1
	s_cmp_eq_u64 vcc, 0
	s_cselect_b64 s[22:23], -1, 0
	s_cbranch_vccz .LBB0_505
	v_max_f32_e32 v0, v1, v1
	v_max_f32_e32 v42, 0, v0
	v_exp_f32_e64 v44, -v42
	v_add_f32_e32 v146, v146, v42
	v_xor_b32_e32 v0, 0x80000000, v146
	v_pk_add_f32 v[18:19], v[18:19], v[42:43] op_sel_hi:[1,0] neg_lo:[0,1] neg_hi:[0,1]
	v_pk_add_f32 v[2:3], v[2:3], v[42:43] op_sel_hi:[1,0] neg_lo:[0,1] neg_hi:[0,1]
	v_pk_add_f32 v[20:21], v[20:21], v[42:43] op_sel_hi:[1,0] neg_lo:[0,1] neg_hi:[0,1]
	v_pk_add_f32 v[4:5], v[4:5], v[42:43] op_sel_hi:[1,0] neg_lo:[0,1] neg_hi:[0,1]
	v_pk_add_f32 v[22:23], v[22:23], v[42:43] op_sel_hi:[1,0] neg_lo:[0,1] neg_hi:[0,1]
	v_pk_add_f32 v[6:7], v[6:7], v[42:43] op_sel_hi:[1,0] neg_lo:[0,1] neg_hi:[0,1]
	v_pk_add_f32 v[24:25], v[24:25], v[42:43] op_sel_hi:[1,0] neg_lo:[0,1] neg_hi:[0,1]
	v_pk_add_f32 v[8:9], v[8:9], v[42:43] op_sel_hi:[1,0] neg_lo:[0,1] neg_hi:[0,1]
	v_pk_add_f32 v[26:27], v[26:27], v[42:43] op_sel_hi:[1,0] neg_lo:[0,1] neg_hi:[0,1]
	v_pk_add_f32 v[10:11], v[10:11], v[42:43] op_sel_hi:[1,0] neg_lo:[0,1] neg_hi:[0,1]
	v_pk_add_f32 v[28:29], v[28:29], v[42:43] op_sel_hi:[1,0] neg_lo:[0,1] neg_hi:[0,1]
	v_pk_add_f32 v[12:13], v[12:13], v[42:43] op_sel_hi:[1,0] neg_lo:[0,1] neg_hi:[0,1]
	v_pk_add_f32 v[30:31], v[30:31], v[42:43] op_sel_hi:[1,0] neg_lo:[0,1] neg_hi:[0,1]
	v_pk_add_f32 v[14:15], v[14:15], v[42:43] op_sel_hi:[1,0] neg_lo:[0,1] neg_hi:[0,1]
	v_pk_add_f32 v[32:33], v[32:33], v[42:43] op_sel_hi:[1,0] neg_lo:[0,1] neg_hi:[0,1]
	v_pk_add_f32 v[16:17], v[16:17], v[42:43] op_sel_hi:[1,0] neg_lo:[0,1] neg_hi:[0,1]
	v_pk_mul_f32 v[42:43], v[150:151], v[44:45] op_sel_hi:[1,0]
	s_branch .LBB0_506
